# v054 + both wave groups run their GEMM epilogues concurrently (one extra lag-preserving barrier per group per tile)
# speedup vs baseline: 1.0137x; 1.0023x over previous
.LBB0_375:
	v_readfirstlane_b32 vcc_lo, v154
	s_nop 0
	s_cmp_lt_u32 vcc_lo, 0x100
	s_cbranch_scc1 .Lce_y
	s_barrier

.LBB0_386:
	s_add_i32 m0, s98, 0xc000
	ds_read_b128 v[176:179], v229 offset:2048
	ds_read_b128 v[180:183], v229 offset:3072
	ds_read_b128 v[184:187], v229 offset:4096
	ds_read_b128 v[188:191], v229 offset:5120
	ds_read_b128 v[192:195], v229 offset:6144
	ds_read_b128 v[196:199], v229 offset:7168
	global_load_lds_dwordx4 v172, s[0:1]
	s_add_i32 m0, s98, 0xe000
	s_nop 0
	global_load_lds_dwordx4 v174, s[0:1]
	s_waitcnt lgkmcnt(6)
	s_barrier
	s_waitcnt lgkmcnt(0)
	v_mfma_f32_16x16x32_bf16 v[126:129], v[130:133], v[146:149], v[126:129]
	v_mfma_f32_16x16x32_bf16 v[122:125], v[138:141], v[146:149], v[122:125]
	v_mfma_f32_16x16x32_bf16 v[110:113], v[130:133], v[176:179], v[110:113]
	v_mfma_f32_16x16x32_bf16 v[106:109], v[138:141], v[176:179], v[106:109]
	v_mfma_f32_16x16x32_bf16 v[94:97], v[130:133], v[184:187], v[94:97]
	v_mfma_f32_16x16x32_bf16 v[90:93], v[138:141], v[184:187], v[90:93]
	v_mfma_f32_16x16x32_bf16 v[78:81], v[130:133], v[192:195], v[78:81]
	v_mfma_f32_16x16x32_bf16 v[74:77], v[138:141], v[192:195], v[74:77]
	v_mfma_f32_16x16x32_bf16 v[126:129], v[134:137], v[150:153], v[126:129]
	v_mfma_f32_16x16x32_bf16 v[122:125], v[142:145], v[150:153], v[122:125]
	v_mfma_f32_16x16x32_bf16 v[110:113], v[134:137], v[180:183], v[110:113]
	v_mfma_f32_16x16x32_bf16 v[106:109], v[142:145], v[180:183], v[106:109]
	v_mfma_f32_16x16x32_bf16 v[94:97], v[134:137], v[188:191], v[94:97]
	v_mfma_f32_16x16x32_bf16 v[90:93], v[142:145], v[188:191], v[90:93]
	v_mfma_f32_16x16x32_bf16 v[78:81], v[134:137], v[196:199], v[78:81]
	v_mfma_f32_16x16x32_bf16 v[74:77], v[142:145], v[196:199], v[74:77]
	s_barrier
	v_add_u32_e32 v0, 0x14000, v224
	s_add_i32 vcc_lo, s97, 0x10000
	s_mov_b32 m0, vcc_lo
	ds_read_b128 v[200:203], v0
	ds_read_b128 v[230:233], v0 offset:1024
	ds_read_b128 v[234:237], v0 offset:2048
	ds_read_b128 v[238:241], v0 offset:3072
	ds_read_b128 v[242:245], v229 offset:16384
	ds_read_b128 v[246:249], v229 offset:17408
	global_load_lds_dwordx4 v158, s[46:47]
	s_add_i32 m0, vcc_lo, 0x2000
	s_nop 0
	global_load_lds_dwordx4 v162, s[46:47]
	s_waitcnt vmcnt(6)
	s_barrier
	s_waitcnt lgkmcnt(0)
	v_mfma_f32_16x16x32_bf16 v[118:121], v[200:203], v[146:149], v[118:121]
	v_mfma_f32_16x16x32_bf16 v[114:117], v[234:237], v[146:149], v[114:117]
	v_mfma_f32_16x16x32_bf16 v[102:105], v[200:203], v[176:179], v[102:105]
	v_mfma_f32_16x16x32_bf16 v[98:101], v[234:237], v[176:179], v[98:101]
	v_mfma_f32_16x16x32_bf16 v[86:89], v[200:203], v[184:187], v[86:89]
	v_mfma_f32_16x16x32_bf16 v[82:85], v[234:237], v[184:187], v[82:85]
	v_mfma_f32_16x16x32_bf16 v[70:73], v[200:203], v[192:195], v[70:73]
	v_mfma_f32_16x16x32_bf16 v[66:69], v[234:237], v[192:195], v[66:69]
	v_mfma_f32_16x16x32_bf16 v[118:121], v[230:233], v[150:153], v[118:121]
	v_mfma_f32_16x16x32_bf16 v[114:117], v[238:241], v[150:153], v[114:117]
	v_mfma_f32_16x16x32_bf16 v[102:105], v[230:233], v[180:183], v[102:105]
	v_mfma_f32_16x16x32_bf16 v[98:101], v[238:241], v[180:183], v[98:101]
	v_mfma_f32_16x16x32_bf16 v[86:89], v[230:233], v[188:191], v[86:89]
	v_mfma_f32_16x16x32_bf16 v[82:85], v[238:241], v[188:191], v[82:85]
	v_mfma_f32_16x16x32_bf16 v[70:73], v[230:233], v[196:199], v[70:73]
	v_mfma_f32_16x16x32_bf16 v[66:69], v[238:241], v[196:199], v[66:69]
	s_barrier
	s_mov_b32 m0, s98
	ds_read_b128 v[176:179], v229 offset:18432
	ds_read_b128 v[180:183], v229 offset:19456
	ds_read_b128 v[184:187], v229 offset:20480
	ds_read_b128 v[188:191], v229 offset:21504
	ds_read_b128 v[192:195], v229 offset:22528
	ds_read_b128 v[196:199], v229 offset:23552
	global_load_lds_dwordx4 v156, s[44:45]
	s_mov_b32 m0, s99
	s_add_u32 s46, s46, s95
	global_load_lds_dwordx4 v160, s[44:45]
	s_addc_u32 s47, s47, 0
	s_barrier
	s_waitcnt lgkmcnt(0)
	v_mfma_f32_16x16x32_bf16 v[62:65], v[130:133], v[242:245], v[62:65]
	v_mfma_f32_16x16x32_bf16 v[58:61], v[138:141], v[242:245], v[58:61]
	v_mfma_f32_16x16x32_bf16 v[46:49], v[130:133], v[176:179], v[46:49]
	v_mfma_f32_16x16x32_bf16 v[42:45], v[138:141], v[176:179], v[42:45]
	v_mfma_f32_16x16x32_bf16 v[30:33], v[130:133], v[184:187], v[30:33]
	v_mfma_f32_16x16x32_bf16 v[26:29], v[138:141], v[184:187], v[26:29]
	v_mfma_f32_16x16x32_bf16 v[14:17], v[130:133], v[192:195], v[14:17]
	v_mfma_f32_16x16x32_bf16 v[10:13], v[138:141], v[192:195], v[10:13]
	v_mfma_f32_16x16x32_bf16 v[62:65], v[134:137], v[246:249], v[62:65]
	v_mfma_f32_16x16x32_bf16 v[58:61], v[142:145], v[246:249], v[58:61]
	v_mfma_f32_16x16x32_bf16 v[46:49], v[134:137], v[180:183], v[46:49]
	v_mfma_f32_16x16x32_bf16 v[42:45], v[142:145], v[180:183], v[42:45]
	v_mfma_f32_16x16x32_bf16 v[30:33], v[134:137], v[188:191], v[30:33]
	v_mfma_f32_16x16x32_bf16 v[26:29], v[142:145], v[188:191], v[26:29]
	v_mfma_f32_16x16x32_bf16 v[14:17], v[134:137], v[196:199], v[14:17]
	v_mfma_f32_16x16x32_bf16 v[10:13], v[142:145], v[196:199], v[10:13]
	s_barrier
	s_add_i32 vcc_lo, s97, 0x14000
	s_add_i32 vcc_hi, s97, 0x16000
	s_mov_b32 m0, vcc_lo
	s_add_u32 s44, s44, s20
	global_load_lds_dwordx4 v158, s[46:47]
	s_mov_b32 m0, vcc_hi
	s_addc_u32 s45, s45, 0
	global_load_lds_dwordx4 v162, s[46:47]
	v_add_u32_e32 v0, 0x18000, v224
	ds_read_b128 v[130:133], v0
	ds_read_b128 v[134:137], v0 offset:1024
	ds_read_b128 v[138:141], v0 offset:2048
	ds_read_b128 v[142:145], v0 offset:3072
	ds_read_b128 v[146:149], v229 offset:32768
	ds_read_b128 v[150:153], v229 offset:33792
	s_waitcnt vmcnt(6)
	s_barrier
	v_mfma_f32_16x16x32_bf16 v[54:57], v[200:203], v[242:245], v[54:57]
	v_mfma_f32_16x16x32_bf16 v[50:53], v[234:237], v[242:245], v[50:53]
	v_mfma_f32_16x16x32_bf16 v[38:41], v[200:203], v[176:179], v[38:41]
	v_mfma_f32_16x16x32_bf16 v[34:37], v[234:237], v[176:179], v[34:37]
	v_mfma_f32_16x16x32_bf16 v[22:25], v[200:203], v[184:187], v[22:25]
	v_mfma_f32_16x16x32_bf16 v[18:21], v[234:237], v[184:187], v[18:21]
	v_mfma_f32_16x16x32_bf16 v[6:9], v[200:203], v[192:195], v[6:9]
	v_mfma_f32_16x16x32_bf16 v[2:5], v[234:237], v[192:195], v[2:5]
	v_mfma_f32_16x16x32_bf16 v[54:57], v[230:233], v[246:249], v[54:57]
	v_mfma_f32_16x16x32_bf16 v[50:53], v[238:241], v[246:249], v[50:53]
	v_mfma_f32_16x16x32_bf16 v[38:41], v[230:233], v[180:183], v[38:41]
	v_mfma_f32_16x16x32_bf16 v[34:37], v[238:241], v[180:183], v[34:37]
	v_mfma_f32_16x16x32_bf16 v[22:25], v[230:233], v[188:191], v[22:25]
	v_mfma_f32_16x16x32_bf16 v[18:21], v[238:241], v[188:191], v[18:21]
	v_mfma_f32_16x16x32_bf16 v[6:9], v[230:233], v[196:199], v[6:9]
	v_mfma_f32_16x16x32_bf16 v[2:5], v[238:241], v[196:199], v[2:5]
	s_barrier
	s_mov_b32 m0, s94
	ds_read_b128 v[176:179], v229 offset:34816
	ds_read_b128 v[180:183], v229 offset:35840
	ds_read_b128 v[184:187], v229 offset:36864
	ds_read_b128 v[188:191], v229 offset:37888
	ds_read_b128 v[192:195], v229 offset:38912
	ds_read_b128 v[196:199], v229 offset:39936
	global_load_lds_dwordx4 v156, s[44:45]
	s_mov_b32 m0, s65
	s_nop 0
	global_load_lds_dwordx4 v160, s[44:45]
	s_waitcnt lgkmcnt(6)
	s_barrier
	s_waitcnt lgkmcnt(0)
	v_mfma_f32_16x16x32_bf16 v[126:129], v[130:133], v[146:149], v[126:129]
	v_mfma_f32_16x16x32_bf16 v[122:125], v[138:141], v[146:149], v[122:125]
	v_mfma_f32_16x16x32_bf16 v[110:113], v[130:133], v[176:179], v[110:113]
	v_mfma_f32_16x16x32_bf16 v[106:109], v[138:141], v[176:179], v[106:109]
	v_mfma_f32_16x16x32_bf16 v[94:97], v[130:133], v[184:187], v[94:97]
	v_mfma_f32_16x16x32_bf16 v[90:93], v[138:141], v[184:187], v[90:93]
	v_mfma_f32_16x16x32_bf16 v[78:81], v[130:133], v[192:195], v[78:81]
	v_mfma_f32_16x16x32_bf16 v[74:77], v[138:141], v[192:195], v[74:77]
	v_mfma_f32_16x16x32_bf16 v[126:129], v[134:137], v[150:153], v[126:129]
	v_mfma_f32_16x16x32_bf16 v[122:125], v[142:145], v[150:153], v[122:125]
	v_mfma_f32_16x16x32_bf16 v[110:113], v[134:137], v[180:183], v[110:113]
	v_mfma_f32_16x16x32_bf16 v[106:109], v[142:145], v[180:183], v[106:109]
	v_mfma_f32_16x16x32_bf16 v[94:97], v[134:137], v[188:191], v[94:97]
	v_mfma_f32_16x16x32_bf16 v[90:93], v[142:145], v[188:191], v[90:93]
	v_mfma_f32_16x16x32_bf16 v[78:81], v[134:137], v[196:199], v[78:81]
	v_mfma_f32_16x16x32_bf16 v[74:77], v[142:145], v[196:199], v[74:77]
	s_barrier
	s_sub_u32 s46, s46, s95
	s_subb_u32 s47, s47, 0
	v_add_u32_e32 v0, 0x1c000, v224
	s_add_i32 vcc_lo, s97, 0x17f80
	s_add_i32 vcc_hi, s97, 0x19f80
	s_mov_b32 m0, vcc_lo
	ds_read_b128 v[200:203], v0
	ds_read_b128 v[230:233], v0 offset:1024
	ds_read_b128 v[234:237], v0 offset:2048
	ds_read_b128 v[238:241], v0 offset:3072
	ds_read_b128 v[242:245], v229 offset:49152
	ds_read_b128 v[246:249], v229 offset:50176
	global_load_lds_dwordx4 v158, s[46:47] offset:128
	s_mov_b32 m0, vcc_hi
	s_sub_u32 s44, s44, s20
	global_load_lds_dwordx4 v162, s[46:47] offset:128
	s_subb_u32 s45, s45, 0
	s_waitcnt vmcnt(6)
	s_barrier
	s_waitcnt lgkmcnt(0)
	v_mfma_f32_16x16x32_bf16 v[118:121], v[200:203], v[146:149], v[118:121]
	v_mfma_f32_16x16x32_bf16 v[114:117], v[234:237], v[146:149], v[114:117]
	v_mfma_f32_16x16x32_bf16 v[102:105], v[200:203], v[176:179], v[102:105]
	v_mfma_f32_16x16x32_bf16 v[98:101], v[234:237], v[176:179], v[98:101]
	v_mfma_f32_16x16x32_bf16 v[86:89], v[200:203], v[184:187], v[86:89]
	v_mfma_f32_16x16x32_bf16 v[82:85], v[234:237], v[184:187], v[82:85]
	v_mfma_f32_16x16x32_bf16 v[70:73], v[200:203], v[192:195], v[70:73]
	v_mfma_f32_16x16x32_bf16 v[66:69], v[234:237], v[192:195], v[66:69]
	v_mfma_f32_16x16x32_bf16 v[118:121], v[230:233], v[150:153], v[118:121]
	v_mfma_f32_16x16x32_bf16 v[114:117], v[238:241], v[150:153], v[114:117]
	v_mfma_f32_16x16x32_bf16 v[102:105], v[230:233], v[180:183], v[102:105]
	v_mfma_f32_16x16x32_bf16 v[98:101], v[238:241], v[180:183], v[98:101]
	v_mfma_f32_16x16x32_bf16 v[86:89], v[230:233], v[188:191], v[86:89]
	v_mfma_f32_16x16x32_bf16 v[82:85], v[238:241], v[188:191], v[82:85]
	v_mfma_f32_16x16x32_bf16 v[70:73], v[230:233], v[196:199], v[70:73]
	v_mfma_f32_16x16x32_bf16 v[66:69], v[238:241], v[196:199], v[66:69]
	s_barrier
	s_add_i32 m0, s87, 0xffffff80
	ds_read_b128 v[176:179], v229 offset:51200
	ds_read_b128 v[180:183], v229 offset:52224
	ds_read_b128 v[184:187], v229 offset:53248
	ds_read_b128 v[188:191], v229 offset:54272
	ds_read_b128 v[192:195], v229 offset:55296
	ds_read_b128 v[196:199], v229 offset:56320
	global_load_lds_dwordx4 v156, s[44:45] offset:128
	s_add_i32 m0, s29, 0xffffff80
	s_add_u32 s46, s46, s95
	global_load_lds_dwordx4 v160, s[44:45] offset:128
	s_addc_u32 s47, s47, 0
	s_barrier
	s_waitcnt lgkmcnt(0)
	v_mfma_f32_16x16x32_bf16 v[62:65], v[130:133], v[242:245], v[62:65]
	v_mfma_f32_16x16x32_bf16 v[58:61], v[138:141], v[242:245], v[58:61]
	v_mfma_f32_16x16x32_bf16 v[46:49], v[130:133], v[176:179], v[46:49]
	v_mfma_f32_16x16x32_bf16 v[42:45], v[138:141], v[176:179], v[42:45]
	v_mfma_f32_16x16x32_bf16 v[30:33], v[130:133], v[184:187], v[30:33]
	v_mfma_f32_16x16x32_bf16 v[26:29], v[138:141], v[184:187], v[26:29]
	v_mfma_f32_16x16x32_bf16 v[14:17], v[130:133], v[192:195], v[14:17]
	v_mfma_f32_16x16x32_bf16 v[10:13], v[138:141], v[192:195], v[10:13]
	v_mfma_f32_16x16x32_bf16 v[62:65], v[134:137], v[246:249], v[62:65]
	v_mfma_f32_16x16x32_bf16 v[58:61], v[142:145], v[246:249], v[58:61]
	v_mfma_f32_16x16x32_bf16 v[46:49], v[134:137], v[180:183], v[46:49]
	v_mfma_f32_16x16x32_bf16 v[42:45], v[142:145], v[180:183], v[42:45]
	v_mfma_f32_16x16x32_bf16 v[30:33], v[134:137], v[188:191], v[30:33]
	v_mfma_f32_16x16x32_bf16 v[26:29], v[142:145], v[188:191], v[26:29]
	v_mfma_f32_16x16x32_bf16 v[14:17], v[134:137], v[196:199], v[14:17]
	v_mfma_f32_16x16x32_bf16 v[10:13], v[142:145], v[196:199], v[10:13]
	s_barrier
	s_add_i32 vcc_lo, s97, 0x1bf80
	s_add_i32 vcc_hi, s97, 0x1df80
	s_mov_b32 m0, vcc_lo
	s_add_u32 s0, s0, 0x100
	global_load_lds_dwordx4 v158, s[46:47] offset:128
	s_mov_b32 m0, vcc_hi
	s_addc_u32 s1, s1, 0
	global_load_lds_dwordx4 v162, s[46:47] offset:128
	v_add_u32_e32 v0, 0x10000, v224
	ds_read_b128 v[130:133], v0
	ds_read_b128 v[134:137], v0 offset:1024
	ds_read_b128 v[138:141], v0 offset:2048
	ds_read_b128 v[142:145], v0 offset:3072
	ds_read_b128 v[146:149], v229
	ds_read_b128 v[150:153], v229 offset:1024
	s_add_u32 s48, s48, 0x100
	s_addc_u32 s49, s49, 0
	s_cmp_ge_i32 s71, s6
	s_cselect_b64 vcc, -1, 0
	s_mov_b32 s44, s71
	s_add_i32 s71, s44, 2
	s_add_u32 s46, s0, 0x80
	s_addc_u32 s45, s1, 0
	s_cmp_eq_u32 s43, s44
	s_cselect_b32 s44, s72, s46
	s_cselect_b32 s45, s73, s45
	s_cselect_b32 s47, s75, s49
	s_cselect_b32 s46, s74, s48
	s_waitcnt vmcnt(6)
	s_barrier
	v_mfma_f32_16x16x32_bf16 v[54:57], v[200:203], v[242:245], v[54:57]
	v_mfma_f32_16x16x32_bf16 v[50:53], v[234:237], v[242:245], v[50:53]
	v_mfma_f32_16x16x32_bf16 v[38:41], v[200:203], v[176:179], v[38:41]
	v_mfma_f32_16x16x32_bf16 v[34:37], v[234:237], v[176:179], v[34:37]
	v_mfma_f32_16x16x32_bf16 v[22:25], v[200:203], v[184:187], v[22:25]
	v_mfma_f32_16x16x32_bf16 v[18:21], v[234:237], v[184:187], v[18:21]
	v_mfma_f32_16x16x32_bf16 v[6:9], v[200:203], v[192:195], v[6:9]
	v_mfma_f32_16x16x32_bf16 v[2:5], v[234:237], v[192:195], v[2:5]
	v_mfma_f32_16x16x32_bf16 v[54:57], v[230:233], v[246:249], v[54:57]
	v_mfma_f32_16x16x32_bf16 v[50:53], v[238:241], v[246:249], v[50:53]
	v_mfma_f32_16x16x32_bf16 v[38:41], v[230:233], v[180:183], v[38:41]
	v_mfma_f32_16x16x32_bf16 v[34:37], v[238:241], v[180:183], v[34:37]
	v_mfma_f32_16x16x32_bf16 v[22:25], v[230:233], v[188:191], v[22:25]
	v_mfma_f32_16x16x32_bf16 v[18:21], v[238:241], v[188:191], v[18:21]
	v_mfma_f32_16x16x32_bf16 v[6:9], v[230:233], v[196:199], v[6:9]
	v_mfma_f32_16x16x32_bf16 v[2:5], v[238:241], v[196:199], v[2:5]
	s_barrier
	s_cbranch_vccz .LBB0_386
	s_waitcnt lgkmcnt(0)
	v_readfirstlane_b32 vcc_lo, v154
	s_nop 0
	s_cmp_lt_u32 vcc_lo, 0x100
	s_cbranch_scc0 .Lce_x
	s_barrier
.Lce_x:
	s_lshl_b32 s46, s77, 8
	s_cmp_lt_i32 s64, 1
	s_mov_b64 s[0:1], -1
	s_cbranch_scc1 .LBB0_403
